# static trailing-half priority extended to the merge GEMM K loop (all five GEMM loops now)
# baseline (speedup 1.0000x reference)
; #define PG8_STAGE(bufoff, gbase, voff) do { _Pragma("unroll") for (int _i = 0; _i < 2; ++_i) \
;         __builtin_amdgcn_global_load_lds((const unsigned*)((const char*)(gbase) + (voff)[_i]), (PG8_LAS unsigned*)(lds + (bufoff) + ldsw + _i * 8192), 16, 0, 0); } while (0)
; #define PG8_LDA(dst, b, h) do { _Pragma("unroll") for (int m = 0; m < 4; ++m) _Pragma("unroll") for (int k = 0; k < 2; ++k) dst[m][k] = *(const PG8_LAS bf16x8*)(lds + PG8_SA(b, h) + aoff + m * 2048 + k * 1024); } while (0)
; #define PG8_LDB(dst, b, h) do { _Pragma("unroll") for (int n = 0; n < 2; ++n) _Pragma("unroll") for (int k = 0; k < 2; ++k) dst[n][k] = *(const PG8_LAS bf16x8*)(lds + PG8_SB(b, h) + boff + n * 2048 + k * 1024); } while (0)
; #define PG8_MMA(ai, bj, At, Bt) do { __builtin_amdgcn_s_setprio(1); _Pragma("unroll") for (int m = 0; m < 4; ++m) _Pragma("unroll") for (int n = 0; n < 2; ++n) _Pragma("unroll") for (int k = 0; k < 2; ++k) \
;         acc[ai][bj][m][n] = __builtin_amdgcn_mfma_f32_16x16x32_bf16(Bt[n][k], At[m][k], acc[ai][bj][m][n], 0, 0, 0); __builtin_amdgcn_s_setprio(0); } while (0)
; #define PG8_WAIT_V(n) asm volatile("s_waitcnt vmcnt(" #n ")" ::: "memory")
; #define PG8_WAIT_L(n) asm volatile("s_waitcnt lgkmcnt(" #n ")" ::: "memory")
; #define PG8_BAR __builtin_amdgcn_s_barrier()
; #define PG8_SCHED __builtin_amdgcn_sched_barrier(0)
;     __device__ bool next(int i, pg8::Unit& u) const { if (!base.next(i >> 1, u)) return false; u.seg = i & 1; return true; }
; template <class Epi, class Sched, bool ALIGN_EPI = false, bool SP2 = false>
; __device__ __forceinline__ void gemm_phase(PG8_LAS unsigned char* lds, const Gemm g, const Sched& S, const Epi& E) {
;     ...
;         const bool has_next = S.next(ui + 1, nxt);
;         const char* nA = has_next ? (const char*)(nxt.seg ? g.A2 : g.A) + (size_t)nxt.pm * tstep : cA; const char* nB = has_next ? (const char*)(nxt.seg ? g.Bt2 : g.Bt) + (size_t)nxt.pn * tstep : cB;
;     ...
;             PG8_LDB(B0, 0, 0); PG8_LDB(B1, 0, 1); PG8_SCHED; PG8_LDA(At, 0, 0); PG8_STAGE(PG8_SA(1, 1), a1 + hstep, voffA);
;             PG8_WAIT_V(8); PG8_WAIT_L(0); PG8_BAR; PG8_MMA(0, 0, At, B0); PG8_MMA(0, 1, At, B1); PG8_BAR; PG8_SCHED;
;             PG8_LDA(At, 0, 1); PG8_STAGE(PG8_SB(0, 0), b2, voffB); PG8_STAGE(PG8_SB(0, 1), b2 + hstep, voffB); PG8_STAGE(PG8_SA(0, 0), a2, voffA);
.LBB0_604:
	s_ashr_i32 s27, s26, 31
	s_lshl_b64 s[28:29], s[26:27], 19
	s_cmp_eq_u32 s63, 0
	s_cselect_b32 s27, s33, s53
	s_cselect_b32 s25, s35, s54
	s_cselect_b32 s36, s46, s55
	s_cselect_b32 s37, s47, s56
	s_add_u32 s28, s27, s28
	s_addc_u32 s29, s25, s29
	s_and_b64 s[30:31], s[0:1], exec
	s_cselect_b32 s27, s29, s41
	s_cselect_b32 s39, s28, s40
	s_ashr_i32 s25, s24, 31
	s_lshl_b64 s[30:31], s[24:25], 19
	s_add_u32 s30, s36, s30
	s_addc_u32 s31, s37, s31
	s_and_b64 s[36:37], s[0:1], exec
	s_cselect_b32 s25, s31, s43
	s_cselect_b32 s64, s30, s42
	s_add_u32 s40, s40, 0x40080
	s_addc_u32 s41, s41, 0
	s_add_u32 s65, s42, 0x100
	s_addc_u32 s66, s43, 0
	s_mov_b32 s67, -2
	s_cmp_lg_u64 s[12:13], 0
	s_cbranch_scc1 .Lsp5_lead
	s_setprio 1
.Lsp5_lead:
.LBB0_605:
	v_add_u32_e32 v1, s60, v156
	ds_read_b128 v[150:153], v1
	ds_read_b128 v[160:163], v1 offset:1024
	ds_read_b128 v[164:167], v1 offset:2048
	ds_read_b128 v[168:171], v1 offset:3072
	v_add_u32_e32 v1, s61, v156
	ds_read_b128 v[172:175], v1
	ds_read_b128 v[176:179], v1 offset:1024
	ds_read_b128 v[180:183], v1 offset:2048
	ds_read_b128 v[184:187], v1 offset:3072
	s_add_u32 s36, s40, 0xfffc0080
	s_addc_u32 s37, s41, -1
	s_cmp_eq_u32 s67, 12
	s_cselect_b32 s45, s27, s37
	s_cselect_b32 s44, s39, s36
	s_cselect_b32 s43, s25, s66
	s_cselect_b32 s42, s64, s65
	v_lshl_add_u64 v[2:3], s[40:41], 0, v[140:141]
	s_add_i32 m0, s49, 0xc000
	ds_read_b128 v[188:191], v158
	ds_read_b128 v[192:195], v158 offset:1024
	ds_read_b128 v[196:199], v158 offset:2048
	ds_read_b128 v[200:203], v158 offset:3072
	ds_read_b128 v[204:207], v158 offset:4096
	ds_read_b128 v[208:211], v158 offset:5120
	ds_read_b128 v[212:215], v158 offset:6144
	ds_read_b128 v[216:219], v158 offset:7168
	global_load_lds_dwordx4 v[2:3], off
	v_lshl_add_u64 v[2:3], s[40:41], 0, v[142:143]
	s_add_i32 m0, s49, 0xe000
	s_nop 0
	global_load_lds_dwordx4 v[2:3], off
	s_waitcnt vmcnt(8)
	s_waitcnt lgkmcnt(0)
	s_barrier
	s_waitcnt lgkmcnt(0)
	v_mfma_f32_16x16x32_bf16 v[128:131], v[150:153], v[188:191], v[128:131]
	v_mfma_f32_16x16x32_bf16 v[124:127], v[164:167], v[188:191], v[124:127]
	v_mfma_f32_16x16x32_bf16 v[120:123], v[150:153], v[196:199], v[120:123]
	v_mfma_f32_16x16x32_bf16 v[116:119], v[164:167], v[196:199], v[116:119]
	v_mfma_f32_16x16x32_bf16 v[112:115], v[150:153], v[204:207], v[112:115]
	v_mfma_f32_16x16x32_bf16 v[108:111], v[164:167], v[204:207], v[108:111]
	v_mfma_f32_16x16x32_bf16 v[104:107], v[150:153], v[212:215], v[104:107]
	v_mfma_f32_16x16x32_bf16 v[100:103], v[164:167], v[212:215], v[100:103]
	v_mfma_f32_16x16x32_bf16 v[128:131], v[160:163], v[192:195], v[128:131]
	v_mfma_f32_16x16x32_bf16 v[124:127], v[168:171], v[192:195], v[124:127]
	v_mfma_f32_16x16x32_bf16 v[120:123], v[160:163], v[200:203], v[120:123]
	v_mfma_f32_16x16x32_bf16 v[116:119], v[168:171], v[200:203], v[116:119]
	v_mfma_f32_16x16x32_bf16 v[112:115], v[160:163], v[208:211], v[112:115]
	v_mfma_f32_16x16x32_bf16 v[108:111], v[168:171], v[208:211], v[108:111]
	v_mfma_f32_16x16x32_bf16 v[104:107], v[160:163], v[216:219], v[104:107]
	v_mfma_f32_16x16x32_bf16 v[100:103], v[168:171], v[216:219], v[100:103]
	v_mfma_f32_16x16x32_bf16 v[96:99], v[172:175], v[188:191], v[96:99]
	v_mfma_f32_16x16x32_bf16 v[92:95], v[180:183], v[188:191], v[92:95]
	v_mfma_f32_16x16x32_bf16 v[88:91], v[172:175], v[196:199], v[88:91]
	v_mfma_f32_16x16x32_bf16 v[84:87], v[180:183], v[196:199], v[84:87]
	v_mfma_f32_16x16x32_bf16 v[80:83], v[172:175], v[204:207], v[80:83]
	v_mfma_f32_16x16x32_bf16 v[76:79], v[180:183], v[204:207], v[76:79]
	v_mfma_f32_16x16x32_bf16 v[72:75], v[172:175], v[212:215], v[72:75]
	v_mfma_f32_16x16x32_bf16 v[68:71], v[180:183], v[212:215], v[68:71]
	v_mfma_f32_16x16x32_bf16 v[96:99], v[176:179], v[192:195], v[96:99]
	v_mfma_f32_16x16x32_bf16 v[92:95], v[184:187], v[192:195], v[92:95]
	v_mfma_f32_16x16x32_bf16 v[88:91], v[176:179], v[200:203], v[88:91]
	v_mfma_f32_16x16x32_bf16 v[84:87], v[184:187], v[200:203], v[84:87]
	v_mfma_f32_16x16x32_bf16 v[80:83], v[176:179], v[208:211], v[80:83]
	v_mfma_f32_16x16x32_bf16 v[76:79], v[184:187], v[208:211], v[76:79]
	v_mfma_f32_16x16x32_bf16 v[72:75], v[176:179], v[216:219], v[72:75]
	v_mfma_f32_16x16x32_bf16 v[68:71], v[184:187], v[216:219], v[68:71]
	s_barrier
	s_add_i32 s36, s60, s48
	v_lshl_add_u64 v[154:155], s[42:43], 0, v[134:135]
	s_mov_b32 m0, s36
	ds_read_b128 v[188:191], v158 offset:16384
	ds_read_b128 v[192:195], v158 offset:17408
	ds_read_b128 v[196:199], v158 offset:18432
	ds_read_b128 v[200:203], v158 offset:19456
	ds_read_b128 v[204:207], v158 offset:20480
	ds_read_b128 v[208:211], v158 offset:21504
	ds_read_b128 v[212:215], v158 offset:22528
	ds_read_b128 v[216:219], v158 offset:23552
	global_load_lds_dwordx4 v[154:155], off
	s_add_i32 m0, s36, 0x2000
	s_add_u32 s36, s42, 0x40000
	v_lshl_add_u64 v[220:221], s[42:43], 0, v[138:139]
	s_addc_u32 s37, s43, 0
	s_add_i32 s68, s61, s48
	global_load_lds_dwordx4 v[220:221], off
	v_lshl_add_u64 v[2:3], s[36:37], 0, v[134:135]
	s_mov_b32 m0, s68
	v_lshl_add_u64 v[222:223], s[44:45], 0, v[132:133]
	global_load_lds_dwordx4 v[2:3], off
	v_lshl_add_u64 v[2:3], s[36:37], 0, v[138:139]
	s_add_i32 m0, s68, 0x2000
	v_lshl_add_u64 v[224:225], s[44:45], 0, v[136:137]
	global_load_lds_dwordx4 v[2:3], off
	s_mov_b32 m0, s49
	s_nop 0
	global_load_lds_dwordx4 v[222:223], off
	s_mov_b32 m0, s50
	s_nop 0
	global_load_lds_dwordx4 v[224:225], off
	s_waitcnt vmcnt(8)
	s_waitcnt lgkmcnt(0)
	s_barrier
; #define PG8_STAGE(bufoff, gbase, voff) do { _Pragma("unroll") for (int _i = 0; _i < 2; ++_i) \
;         __builtin_amdgcn_global_load_lds((const unsigned*)((const char*)(gbase) + (voff)[_i]), (PG8_LAS unsigned*)(lds + (bufoff) + ldsw + _i * 8192), 16, 0, 0); } while (0)
; #define PG8_LDA(dst, b, h) do { _Pragma("unroll") for (int m = 0; m < 4; ++m) _Pragma("unroll") for (int k = 0; k < 2; ++k) dst[m][k] = *(const PG8_LAS bf16x8*)(lds + PG8_SA(b, h) + aoff + m * 2048 + k * 1024); } while (0)
; #define PG8_LDB(dst, b, h) do { _Pragma("unroll") for (int n = 0; n < 2; ++n) _Pragma("unroll") for (int k = 0; k < 2; ++k) dst[n][k] = *(const PG8_LAS bf16x8*)(lds + PG8_SB(b, h) + boff + n * 2048 + k * 1024); } while (0)
; #define PG8_MMA(ai, bj, At, Bt) do { __builtin_amdgcn_s_setprio(1); _Pragma("unroll") for (int m = 0; m < 4; ++m) _Pragma("unroll") for (int n = 0; n < 2; ++n) _Pragma("unroll") for (int k = 0; k < 2; ++k) \
;         acc[ai][bj][m][n] = __builtin_amdgcn_mfma_f32_16x16x32_bf16(Bt[n][k], At[m][k], acc[ai][bj][m][n], 0, 0, 0); __builtin_amdgcn_s_setprio(0); } while (0)
; #define PG8_WAIT_V(n) asm volatile("s_waitcnt vmcnt(" #n ")" ::: "memory")
; #define PG8_WAIT_L(n) asm volatile("s_waitcnt lgkmcnt(" #n ")" ::: "memory")
; #define PG8_BAR __builtin_amdgcn_s_barrier()
; #define PG8_SCHED __builtin_amdgcn_sched_barrier(0)
; template <class Epi, class Sched, bool ALIGN_EPI = false, bool SP2 = false>
; __device__ __forceinline__ void gemm_phase(PG8_LAS unsigned char* lds, const Gemm g, const Sched& S, const Epi& E) {
;     ...
;             PG8_WAIT_V(8); PG8_WAIT_L(0); PG8_BAR; PG8_MMA(1, 0, At, B0); PG8_MMA(1, 1, At, B1); PG8_BAR; PG8_SCHED;
;             PG8_LDB(B0, 1, 0); PG8_LDB(B1, 1, 1); PG8_SCHED; PG8_LDA(At, 1, 0); PG8_STAGE(PG8_SA(0, 1), a2 + hstep, voffA);
;             PG8_WAIT_V(8); PG8_WAIT_L(0); PG8_BAR; PG8_MMA(0, 0, At, B0); PG8_MMA(0, 1, At, B1); PG8_BAR; PG8_SCHED;
	s_waitcnt lgkmcnt(0)
	v_mfma_f32_16x16x32_bf16 v[64:67], v[150:153], v[188:191], v[64:67]
	v_mfma_f32_16x16x32_bf16 v[60:63], v[164:167], v[188:191], v[60:63]
	v_mfma_f32_16x16x32_bf16 v[56:59], v[150:153], v[196:199], v[56:59]
	v_mfma_f32_16x16x32_bf16 v[52:55], v[164:167], v[196:199], v[52:55]
	v_mfma_f32_16x16x32_bf16 v[48:51], v[150:153], v[204:207], v[48:51]
	v_mfma_f32_16x16x32_bf16 v[44:47], v[164:167], v[204:207], v[44:47]
	v_mfma_f32_16x16x32_bf16 v[40:43], v[150:153], v[212:215], v[40:43]
	v_mfma_f32_16x16x32_bf16 v[36:39], v[164:167], v[212:215], v[36:39]
	v_mfma_f32_16x16x32_bf16 v[64:67], v[160:163], v[192:195], v[64:67]
	v_mfma_f32_16x16x32_bf16 v[60:63], v[168:171], v[192:195], v[60:63]
	v_mfma_f32_16x16x32_bf16 v[56:59], v[160:163], v[200:203], v[56:59]
	v_mfma_f32_16x16x32_bf16 v[52:55], v[168:171], v[200:203], v[52:55]
	v_mfma_f32_16x16x32_bf16 v[48:51], v[160:163], v[208:211], v[48:51]
	v_mfma_f32_16x16x32_bf16 v[44:47], v[168:171], v[208:211], v[44:47]
	v_mfma_f32_16x16x32_bf16 v[40:43], v[160:163], v[216:219], v[40:43]
	v_mfma_f32_16x16x32_bf16 v[36:39], v[168:171], v[216:219], v[36:39]
	v_mfma_f32_16x16x32_bf16 v[32:35], v[172:175], v[188:191], v[32:35]
	v_mfma_f32_16x16x32_bf16 v[28:31], v[180:183], v[188:191], v[28:31]
	v_mfma_f32_16x16x32_bf16 v[24:27], v[172:175], v[196:199], v[24:27]
	v_mfma_f32_16x16x32_bf16 v[20:23], v[180:183], v[196:199], v[20:23]
	v_mfma_f32_16x16x32_bf16 v[16:19], v[172:175], v[204:207], v[16:19]
	v_mfma_f32_16x16x32_bf16 v[12:15], v[180:183], v[204:207], v[12:15]
	v_mfma_f32_16x16x32_bf16 v[8:11], v[172:175], v[212:215], v[8:11]
	v_mfma_f32_16x16x32_bf16 v[2:5], v[180:183], v[212:215], v[4:7]
	v_mfma_f32_16x16x32_bf16 v[32:35], v[176:179], v[192:195], v[32:35]
	v_mfma_f32_16x16x32_bf16 v[28:31], v[184:187], v[192:195], v[28:31]
	v_mfma_f32_16x16x32_bf16 v[24:27], v[176:179], v[200:203], v[24:27]
	v_mfma_f32_16x16x32_bf16 v[20:23], v[184:187], v[200:203], v[20:23]
	v_mfma_f32_16x16x32_bf16 v[16:19], v[176:179], v[208:211], v[16:19]
	v_mfma_f32_16x16x32_bf16 v[12:15], v[184:187], v[208:211], v[12:15]
	v_mfma_f32_16x16x32_bf16 v[8:11], v[176:179], v[216:219], v[8:11]
	v_mfma_f32_16x16x32_bf16 v[2:5], v[184:187], v[216:219], v[2:5]
	s_barrier
	s_add_i32 s68, 0, 0x18000
	v_add_u32_e32 v1, s68, v156
	s_add_i32 s69, 0, 0x1c000
	ds_read_b128 v[150:153], v1
	ds_read_b128 v[160:163], v1 offset:1024
	ds_read_b128 v[164:167], v1 offset:2048
	ds_read_b128 v[168:171], v1 offset:3072
	v_add_u32_e32 v1, s69, v156
	ds_read_b128 v[172:175], v1
	ds_read_b128 v[176:179], v1 offset:1024
	ds_read_b128 v[180:183], v1 offset:2048
	ds_read_b128 v[184:187], v1 offset:3072
	s_add_u32 s36, s44, 0x40000
	s_addc_u32 s37, s45, 0
	s_mov_b32 m0, s51
	v_lshl_add_u64 v[6:7], s[36:37], 0, v[132:133]
	ds_read_b128 v[188:191], v158 offset:32768
	ds_read_b128 v[192:195], v158 offset:33792
	ds_read_b128 v[196:199], v158 offset:34816
	ds_read_b128 v[200:203], v158 offset:35840
	ds_read_b128 v[204:207], v158 offset:36864
	ds_read_b128 v[208:211], v158 offset:37888
	ds_read_b128 v[212:215], v158 offset:38912
	ds_read_b128 v[216:219], v158 offset:39936
	global_load_lds_dwordx4 v[6:7], off
	v_lshl_add_u64 v[6:7], s[36:37], 0, v[136:137]
	s_mov_b32 m0, s52
	s_nop 0
	global_load_lds_dwordx4 v[6:7], off
	s_waitcnt vmcnt(8)
	s_waitcnt lgkmcnt(0)
	s_barrier
	s_waitcnt lgkmcnt(0)
	v_mfma_f32_16x16x32_bf16 v[128:131], v[150:153], v[188:191], v[128:131]
	v_mfma_f32_16x16x32_bf16 v[124:127], v[164:167], v[188:191], v[124:127]
	v_mfma_f32_16x16x32_bf16 v[120:123], v[150:153], v[196:199], v[120:123]
	v_mfma_f32_16x16x32_bf16 v[116:119], v[164:167], v[196:199], v[116:119]
	v_mfma_f32_16x16x32_bf16 v[112:115], v[150:153], v[204:207], v[112:115]
	v_mfma_f32_16x16x32_bf16 v[108:111], v[164:167], v[204:207], v[108:111]
	v_mfma_f32_16x16x32_bf16 v[104:107], v[150:153], v[212:215], v[104:107]
	v_mfma_f32_16x16x32_bf16 v[100:103], v[164:167], v[212:215], v[100:103]
	v_mfma_f32_16x16x32_bf16 v[128:131], v[160:163], v[192:195], v[128:131]
	v_mfma_f32_16x16x32_bf16 v[124:127], v[168:171], v[192:195], v[124:127]
	v_mfma_f32_16x16x32_bf16 v[120:123], v[160:163], v[200:203], v[120:123]
	v_mfma_f32_16x16x32_bf16 v[116:119], v[168:171], v[200:203], v[116:119]
	v_mfma_f32_16x16x32_bf16 v[112:115], v[160:163], v[208:211], v[112:115]
	v_mfma_f32_16x16x32_bf16 v[108:111], v[168:171], v[208:211], v[108:111]
	v_mfma_f32_16x16x32_bf16 v[104:107], v[160:163], v[216:219], v[104:107]
	v_mfma_f32_16x16x32_bf16 v[100:103], v[168:171], v[216:219], v[100:103]
	v_mfma_f32_16x16x32_bf16 v[96:99], v[172:175], v[188:191], v[96:99]
	v_mfma_f32_16x16x32_bf16 v[92:95], v[180:183], v[188:191], v[92:95]
	v_mfma_f32_16x16x32_bf16 v[88:91], v[172:175], v[196:199], v[88:91]
	v_mfma_f32_16x16x32_bf16 v[84:87], v[180:183], v[196:199], v[84:87]
	v_mfma_f32_16x16x32_bf16 v[80:83], v[172:175], v[204:207], v[80:83]
	v_mfma_f32_16x16x32_bf16 v[76:79], v[180:183], v[204:207], v[76:79]
	v_mfma_f32_16x16x32_bf16 v[72:75], v[172:175], v[212:215], v[72:75]
	v_mfma_f32_16x16x32_bf16 v[68:71], v[180:183], v[212:215], v[68:71]
	v_mfma_f32_16x16x32_bf16 v[96:99], v[176:179], v[192:195], v[96:99]
	v_mfma_f32_16x16x32_bf16 v[92:95], v[184:187], v[192:195], v[92:95]
	v_mfma_f32_16x16x32_bf16 v[88:91], v[176:179], v[200:203], v[88:91]
	v_mfma_f32_16x16x32_bf16 v[84:87], v[184:187], v[200:203], v[84:87]
	v_mfma_f32_16x16x32_bf16 v[80:83], v[176:179], v[208:211], v[80:83]
	v_mfma_f32_16x16x32_bf16 v[76:79], v[184:187], v[208:211], v[76:79]
	v_mfma_f32_16x16x32_bf16 v[72:75], v[176:179], v[216:219], v[72:75]
	v_mfma_f32_16x16x32_bf16 v[68:71], v[184:187], v[216:219], v[68:71]
	s_barrier
; #define PG8_STAGE(bufoff, gbase, voff) do { _Pragma("unroll") for (int _i = 0; _i < 2; ++_i) \
;         __builtin_amdgcn_global_load_lds((const unsigned*)((const char*)(gbase) + (voff)[_i]), (PG8_LAS unsigned*)(lds + (bufoff) + ldsw + _i * 8192), 16, 0, 0); } while (0)
; #define PG8_LDA(dst, b, h) do { _Pragma("unroll") for (int m = 0; m < 4; ++m) _Pragma("unroll") for (int k = 0; k < 2; ++k) dst[m][k] = *(const PG8_LAS bf16x8*)(lds + PG8_SA(b, h) + aoff + m * 2048 + k * 1024); } while (0)
; #define PG8_MMA(ai, bj, At, Bt) do { __builtin_amdgcn_s_setprio(1); _Pragma("unroll") for (int m = 0; m < 4; ++m) _Pragma("unroll") for (int n = 0; n < 2; ++n) _Pragma("unroll") for (int k = 0; k < 2; ++k) \
;         acc[ai][bj][m][n] = __builtin_amdgcn_mfma_f32_16x16x32_bf16(Bt[n][k], At[m][k], acc[ai][bj][m][n], 0, 0, 0); __builtin_amdgcn_s_setprio(0); } while (0)
; #define PG8_WAIT_V(n) asm volatile("s_waitcnt vmcnt(" #n ")" ::: "memory")
; #define PG8_WAIT_L(n) asm volatile("s_waitcnt lgkmcnt(" #n ")" ::: "memory")
; #define PG8_BAR __builtin_amdgcn_s_barrier()
; #define PG8_SCHED __builtin_amdgcn_sched_barrier(0)
; template <class Epi, class Sched, bool ALIGN_EPI = false, bool SP2 = false>
; __device__ __forceinline__ void gemm_phase(PG8_LAS unsigned char* lds, const Gemm g, const Sched& S, const Epi& E) {
;     ...
;             PG8_LDA(At, 1, 1); PG8_STAGE(PG8_SB(1, 0), b3, voffB); PG8_STAGE(PG8_SB(1, 1), b3 + hstep, voffB); PG8_STAGE(PG8_SA(1, 0), a3, voffA);
;             PG8_WAIT_V(8); PG8_WAIT_L(0); PG8_BAR; PG8_MMA(1, 0, At, B0); PG8_MMA(1, 1, At, B1); PG8_BAR; PG8_SCHED;
;     ...
;         if constexpr (ALIGN_EPI) { if (wr == 0) PG8_BAR; }
	s_add_i32 s36, s68, s48
	v_lshl_add_u64 v[6:7], v[154:155], 0, s[10:11]
	s_mov_b32 m0, s36
	ds_read_b128 v[188:191], v158 offset:49152
	ds_read_b128 v[192:195], v158 offset:50176
	ds_read_b128 v[196:199], v158 offset:51200
	ds_read_b128 v[200:203], v158 offset:52224
	ds_read_b128 v[204:207], v158 offset:53248
	ds_read_b128 v[208:211], v158 offset:54272
	ds_read_b128 v[212:215], v158 offset:55296
	ds_read_b128 v[216:219], v158 offset:56320
	global_load_lds_dwordx4 v[6:7], off
	s_add_i32 m0, s36, 0x2000
	s_add_u32 s36, s42, 0x40080
	v_lshl_add_u64 v[6:7], v[220:221], 0, s[10:11]
	s_addc_u32 s37, s43, 0
	s_add_i32 s42, s69, s48
	global_load_lds_dwordx4 v[6:7], off
	v_lshl_add_u64 v[6:7], s[36:37], 0, v[134:135]
	s_mov_b32 m0, s42
	s_nop 0
	global_load_lds_dwordx4 v[6:7], off
	v_lshl_add_u64 v[6:7], s[36:37], 0, v[138:139]
	s_add_i32 m0, s42, 0x2000
	s_nop 0
	global_load_lds_dwordx4 v[6:7], off
	v_lshl_add_u64 v[6:7], v[222:223], 0, s[10:11]
	s_mov_b32 m0, s57
	s_nop 0
	global_load_lds_dwordx4 v[6:7], off
	v_lshl_add_u64 v[6:7], v[224:225], 0, s[10:11]
	s_mov_b32 m0, s58
	s_nop 0
	global_load_lds_dwordx4 v[6:7], off
	s_waitcnt vmcnt(8)
	s_waitcnt lgkmcnt(0)
	s_barrier
	s_waitcnt lgkmcnt(0)
	v_mfma_f32_16x16x32_bf16 v[64:67], v[150:153], v[188:191], v[64:67]
	v_mfma_f32_16x16x32_bf16 v[60:63], v[164:167], v[188:191], v[60:63]
	v_mfma_f32_16x16x32_bf16 v[56:59], v[150:153], v[196:199], v[56:59]
	v_mfma_f32_16x16x32_bf16 v[52:55], v[164:167], v[196:199], v[52:55]
	v_mfma_f32_16x16x32_bf16 v[48:51], v[150:153], v[204:207], v[48:51]
	v_mfma_f32_16x16x32_bf16 v[44:47], v[164:167], v[204:207], v[44:47]
	v_mfma_f32_16x16x32_bf16 v[40:43], v[150:153], v[212:215], v[40:43]
	v_mfma_f32_16x16x32_bf16 v[36:39], v[164:167], v[212:215], v[36:39]
	v_mfma_f32_16x16x32_bf16 v[64:67], v[160:163], v[192:195], v[64:67]
	v_mfma_f32_16x16x32_bf16 v[60:63], v[168:171], v[192:195], v[60:63]
	v_mfma_f32_16x16x32_bf16 v[56:59], v[160:163], v[200:203], v[56:59]
	v_mfma_f32_16x16x32_bf16 v[52:55], v[168:171], v[200:203], v[52:55]
	v_mfma_f32_16x16x32_bf16 v[48:51], v[160:163], v[208:211], v[48:51]
	v_mfma_f32_16x16x32_bf16 v[44:47], v[168:171], v[208:211], v[44:47]
	v_mfma_f32_16x16x32_bf16 v[40:43], v[160:163], v[216:219], v[40:43]
	v_mfma_f32_16x16x32_bf16 v[36:39], v[168:171], v[216:219], v[36:39]
	v_mfma_f32_16x16x32_bf16 v[32:35], v[172:175], v[188:191], v[32:35]
	v_mfma_f32_16x16x32_bf16 v[28:31], v[180:183], v[188:191], v[28:31]
	v_mfma_f32_16x16x32_bf16 v[24:27], v[172:175], v[196:199], v[24:27]
	v_mfma_f32_16x16x32_bf16 v[20:23], v[180:183], v[196:199], v[20:23]
	v_mfma_f32_16x16x32_bf16 v[16:19], v[172:175], v[204:207], v[16:19]
	v_mfma_f32_16x16x32_bf16 v[12:15], v[180:183], v[204:207], v[12:15]
	v_mfma_f32_16x16x32_bf16 v[6:9], v[172:175], v[212:215], v[8:11]
	v_mfma_f32_16x16x32_bf16 v[2:5], v[180:183], v[212:215], v[2:5]
	v_mfma_f32_16x16x32_bf16 v[32:35], v[176:179], v[192:195], v[32:35]
	v_mfma_f32_16x16x32_bf16 v[28:31], v[184:187], v[192:195], v[28:31]
	v_mfma_f32_16x16x32_bf16 v[24:27], v[176:179], v[200:203], v[24:27]
	v_mfma_f32_16x16x32_bf16 v[20:23], v[184:187], v[200:203], v[20:23]
	v_mfma_f32_16x16x32_bf16 v[16:19], v[176:179], v[208:211], v[16:19]
	v_mfma_f32_16x16x32_bf16 v[12:15], v[184:187], v[208:211], v[12:15]
	v_mfma_f32_16x16x32_bf16 v[8:11], v[176:179], v[216:219], v[6:9]
	v_mfma_f32_16x16x32_bf16 v[4:7], v[184:187], v[216:219], v[2:5]
	s_barrier
	s_add_i32 s67, s67, 2
	s_add_u32 s40, s40, 0x100
	s_addc_u32 s41, s41, 0
	s_add_u32 s65, s65, 0x100
	s_addc_u32 s66, s66, 0
	s_cmp_gt_u32 s67, 13
	s_cbranch_scc0 .LBB0_605
	s_setprio 0
	s_and_b64 vcc, exec, s[12:13]
	s_cbranch_vccz .LBB0_608
	s_barrier
